# grid barrier: the per-XCD last arrivers also wait on the top-level arrival counter (generation word no longer polled)
# speedup vs baseline: 1.0059x; 1.0016x over previous
.LBB0_891:
	s_or_b64 exec, exec, s[8:9]
	s_waitcnt vmcnt(0)
	v_readfirstlane_b32 s6, v3
	v_sub_u32_e32 v4, 0, v2
	s_mov_b64 s[8:9], -1
	v_add_u32_e32 v3, s6, v0
	v_cvt_f32_u32_e32 v0, v2
	v_readlane_b32 s6, v252, 51
	v_readlane_b32 s7, v252, 52
	v_rcp_iflag_f32_e32 v0, v0
	s_nop 0
	v_mul_f32_e32 v0, 0x4f7ffffe, v0
	v_cvt_u32_f32_e32 v0, v0
	v_mul_lo_u32 v4, v4, v0
	v_mul_hi_u32 v4, v0, v4
	v_add_u32_e32 v0, v0, v4
	v_mul_hi_u32 v0, v3, v0
	v_mul_lo_u32 v4, v0, v2
	v_sub_u32_e32 v4, v3, v4
	v_cmp_ge_u32_e32 vcc, v4, v2
	v_add_u32_e32 v5, 1, v0
	v_add_u32_e32 v3, 1, v3
	v_cndmask_b32_e32 v0, v0, v5, vcc
	v_sub_u32_e32 v5, v4, v2
	v_cndmask_b32_e32 v4, v4, v5, vcc
	v_cmp_ge_u32_e32 vcc, v4, v2
	v_add_u32_e32 v4, 1, v0
	s_nop 0
	v_cndmask_b32_e32 v0, v0, v4, vcc
	v_mul_lo_u32 v4, v2, v0
	v_add_u32_e32 v2, v4, v2
	v_cmp_ne_u32_e32 vcc, v3, v2
	v_mov_b32_e32 v7, v2
	v_mov_b64_e32 v[2:3], s[6:7]
	s_and_saveexec_b64 s[6:7], vcc
	s_cbranch_execz .LBB0_903
	v_mov_b32_e32 v0, -1
	v_readlane_b32 s8, v252, 49
	v_readlane_b32 s9, v252, 50
	s_mov_b64 s[10:11], 0
	s_nop 3
	global_load_dword v2, v1, s[8:9] sc1
	s_waitcnt vmcnt(0)
	v_sub_u32_e32 v2, v2, v7
	v_ashrrev_i32_e32 v2, 31, v2
	v_cmp_eq_u32_e32 vcc, v2, v0
	s_and_saveexec_b64 s[8:9], vcc
	s_cbranch_execz .LBB0_902
	s_mov_b32 s18, 1
	s_branch .LBB0_895

.LBB0_897:
	v_readlane_b32 s14, v252, 49
	v_readlane_b32 s15, v252, 50
	s_add_i32 s18, s18, 1
	s_mov_b64 s[16:17], -1
	s_nop 2
	global_load_dword v2, v1, s[14:15] sc1
	s_waitcnt vmcnt(0)
	v_sub_u32_e32 v2, v2, v7
	v_ashrrev_i32_e32 v2, 31, v2
	v_cmp_ne_u32_e32 vcc, v2, v0
	s_orn2_b64 s[14:15], vcc, exec
	s_branch .LBB0_894
